# v25 + P3 RMSNorm 16-lane butterfly via DPP moves instead of 16 ds_bpermute
# speedup vs baseline: 1.0064x; 1.0032x over previous
; #define LAS __attribute__((address_space(3)))
; __device__ __forceinline__ f32x4 mfma16(bf16x8 a, bf16x8 b, f32x4 c) { return __builtin_amdgcn_mfma_f32_16x16x32_bf16(a, b, c, 0, 0, 0); }
; #define LBAR() asm volatile("s_waitcnt lgkmcnt(0)\n\ts_barrier" ::: "memory")
; #define OPQ_ALL() do { asm volatile("" : "+v"(g), "+v"(l15), "+v"(q4), "+v"(p)); } while (0)
; __device__ __forceinline__ void ret_phase(const Params& P, LAS unsigned char* lds, int tid, int lane, int wave, int bid, int G) {
;     ...
;         LBAR();
;         OPQ_ALL();
;         f32x4 o[8];
; #pragma unroll
;         for (int t = 0; t < 8; ++t) o[t] = (f32x4){0.f, 0.f, 0.f, 0.f};
;         u32x4 grv[4];
; #pragma unroll
;         for (int it = 0; it < 4; ++it) grv[it] = *(const u32x4*)(GR + (tokc + w16 + 4 * it + g) * 512 + h * 128 + 8 * l15);
; #pragma unroll
;         for (int t = 0; t < 8; ++t)
; #pragma unroll
;             for (int ks = 0; ks < 4; ++ks) { o[t] = mfma16(qf[ks], *(const LAS bf16x8*)(Qt + off256(16 * t + l15, 4 * ks + g)), o[t]); }
;         float wb[4];
; #pragma unroll
;         for (int i = 0; i < 4; ++i) { const float pos = (float)(w16 + 4 * g + i); const float wf = exp2f(lgf2 * (pos + 1.f)); wb[i] = exp2f(lgb2 * (128.f - pos)); const float rt = wf / wb[i];
; #pragma unroll
;             for (int t = 0; t < 8; ++t) o[t][i] *= rt; }
.LBB0_383:
	s_waitcnt lgkmcnt(0)
	s_barrier
	s_ashr_i32 s41, s40, 31
	v_lshlrev_b32_e32 v66, 2, v1
	v_and_b32_e32 v86, 12, v66
	v_bfe_u32 v87, v1, 2, 2
	v_lshl_add_u32 v88, v1, 8, 0
	v_bitop3_b32 v66, v86, v118, v87 bitop3:0x36
	v_lshl_add_u32 v135, v66, 4, v88
	ds_read_b128 v[66:69], v135
	ds_read_b128 v[70:73], v135 offset:4096
	v_add_u32_e32 v74, 4, v118
	v_bitop3_b32 v74, v86, v74, v87 bitop3:0x36
	v_lshl_add_u32 v168, v74, 4, v88
	s_waitcnt lgkmcnt(1)
	v_mfma_f32_16x16x32_bf16 v[66:69], v[58:61], v[66:69], 0
	ds_read_b128 v[74:77], v168
	ds_read_b128 v[78:81], v168 offset:4096
	v_lshl_add_u32 v102, v118, 2, s46
	v_cvt_f32_i32_e32 v103, v102
	s_waitcnt lgkmcnt(1)
	v_mfma_f32_16x16x32_bf16 v[66:69], v[54:57], v[74:77], v[66:69]
	v_add_u32_e32 v74, 8, v118
	v_bitop3_b32 v74, v86, v74, v87 bitop3:0x36
	v_lshl_add_u32 v169, v74, 4, v88
	ds_read_b128 v[74:77], v169
	ds_read_b128 v[82:85], v169 offset:4096
	s_waitcnt lgkmcnt(1)
	v_mfma_f32_16x16x32_bf16 v[66:69], v[62:65], v[74:77], v[66:69]
	v_add_u32_e32 v74, 12, v118
	v_bitop3_b32 v74, v86, v74, v87 bitop3:0x36
	v_lshl_add_u32 v170, v74, 4, v88
	ds_read_b128 v[74:77], v170
	ds_read_b128 v[86:89], v170 offset:4096
	s_waitcnt lgkmcnt(1)
	v_mfma_f32_16x16x32_bf16 v[74:77], v[50:53], v[74:77], v[66:69]
	v_add_f32_e32 v119, 1.0, v103
	v_mul_f32_e32 v171, v105, v119
	v_cmp_gt_f32_e32 vcc, s52, v171
	v_mfma_f32_16x16x32_bf16 v[66:69], v[58:61], v[70:73], 0
	v_sub_f32_e32 v103, 0x43000000, v103
	v_cndmask_b32_e32 v171, 0, v133, vcc
	s_lshl_b64 s[40:41], s[40:41], 7
	v_mfma_f32_16x16x32_bf16 v[66:69], v[54:57], v[78:81], v[66:69]
	v_mfma_f32_16x16x32_bf16 v[66:69], v[62:65], v[82:85], v[66:69]
	s_waitcnt lgkmcnt(0)
	v_mfma_f32_16x16x32_bf16 v[70:73], v[50:53], v[86:89], v[66:69]
	s_nop 5
	ds_read_b128 v[66:69], v135 offset:8192
	ds_read_b128 v[78:81], v135 offset:12288
	ds_read_b128 v[82:85], v168 offset:8192
	ds_read_b128 v[86:89], v168 offset:12288
	s_waitcnt lgkmcnt(3)
	v_mfma_f32_16x16x32_bf16 v[66:69], v[58:61], v[66:69], 0
	s_waitcnt lgkmcnt(1)
	v_mfma_f32_16x16x32_bf16 v[66:69], v[54:57], v[82:85], v[66:69]
	ds_read_b128 v[82:85], v169 offset:8192
	ds_read_b128 v[90:93], v169 offset:12288
	s_waitcnt lgkmcnt(1)
	v_mfma_f32_16x16x32_bf16 v[66:69], v[62:65], v[82:85], v[66:69]
	ds_read_b128 v[82:85], v170 offset:8192
	ds_read_b128 v[94:97], v170 offset:12288
	ds_read_b128 v[98:101], v135 offset:16384
	ds_read_b128 v[122:125], v135 offset:20480
	s_waitcnt lgkmcnt(3)
	v_mfma_f32_16x16x32_bf16 v[82:85], v[50:53], v[82:85], v[66:69]
	v_mfma_f32_16x16x32_bf16 v[66:69], v[58:61], v[78:81], 0
	v_mfma_f32_16x16x32_bf16 v[66:69], v[54:57], v[86:89], v[66:69]
	ds_read_b128 v[86:89], v168 offset:16384
	ds_read_b128 v[136:139], v168 offset:20480
	ds_read_b128 v[140:143], v169 offset:16384
	ds_read_b128 v[144:147], v169 offset:20480
	v_mfma_f32_16x16x32_bf16 v[66:69], v[62:65], v[90:93], v[66:69]
	ds_read_b128 v[90:93], v170 offset:16384
	ds_read_b128 v[148:151], v170 offset:20480
	ds_read_b128 v[152:155], v135 offset:24576
	ds_read_b128 v[156:159], v135 offset:28672
	s_waitcnt lgkmcnt(10)
	v_mfma_f32_16x16x32_bf16 v[78:81], v[50:53], v[94:97], v[66:69]
	s_nop 2
	ds_read_b128 v[66:69], v168 offset:24576
	ds_read_b128 v[160:163], v168 offset:28672
	s_waitcnt lgkmcnt(11)
	v_mfma_f32_16x16x32_bf16 v[94:97], v[58:61], v[98:101], 0
	ds_read_b128 v[98:101], v169 offset:24576
	ds_read_b128 v[164:167], v169 offset:28672
	s_waitcnt lgkmcnt(11)
	v_mfma_f32_16x16x32_bf16 v[86:89], v[54:57], v[86:89], v[94:97]
	s_nop 3
	v_cndmask_b32_e32 v94, 0, v132, vcc
	v_fmac_f32_e32 v94, v105, v119
	v_exp_f32_e32 v119, v94
	s_waitcnt lgkmcnt(9)
	v_mfma_f32_16x16x32_bf16 v[86:89], v[62:65], v[140:143], v[86:89]
	ds_read_b128 v[94:97], v170 offset:24576
	ds_read_b128 v[140:143], v170 offset:28672
	v_ldexp_f32 v119, v119, v171
	v_mul_f32_e32 v171, v104, v103
	v_cmp_gt_f32_e32 vcc, s52, v171
	s_waitcnt lgkmcnt(9)
	v_mfma_f32_16x16x32_bf16 v[90:93], v[50:53], v[90:93], v[86:89]
	v_mfma_f32_16x16x32_bf16 v[86:89], v[58:61], v[122:125], 0
	v_cndmask_b32_e32 v122, 0, v132, vcc
	v_fmac_f32_e32 v122, v104, v103
	v_or_b32_e32 v103, 1, v102
	v_cvt_f32_i32_e32 v103, v103
	v_cndmask_b32_e32 v123, 0, v133, vcc
	v_mfma_f32_16x16x32_bf16 v[86:89], v[54:57], v[136:139], v[86:89]
	v_exp_f32_e32 v122, v122
	v_add_f32_e32 v124, 1.0, v103
	v_mul_f32_e32 v125, v105, v124
	v_cmp_gt_f32_e32 vcc, s52, v125
	s_waitcnt lgkmcnt(7)
	v_mfma_f32_16x16x32_bf16 v[136:139], v[58:61], v[152:155], 0
	v_ldexp_f32 v122, v122, v123
	v_cndmask_b32_e32 v125, 0, v132, vcc
	v_fmac_f32_e32 v125, v105, v124
	v_exp_f32_e32 v124, v125
	s_waitcnt lgkmcnt(5)
	v_mfma_f32_16x16x32_bf16 v[66:69], v[54:57], v[66:69], v[136:139]
	v_cndmask_b32_e32 v123, 0, v133, vcc
	v_sub_f32_e32 v103, 0x43000000, v103
	v_ldexp_f32 v124, v124, v123
	v_mul_f32_e32 v123, v104, v103
	v_cmp_gt_f32_e32 vcc, s52, v123
	s_waitcnt lgkmcnt(3)
	v_mfma_f32_16x16x32_bf16 v[66:69], v[62:65], v[98:101], v[66:69]
	v_div_scale_f32 v99, s[0:1], v122, v122, v119
	v_cndmask_b32_e32 v98, 0, v132, vcc
	v_fmac_f32_e32 v98, v104, v103
	v_exp_f32_e32 v98, v98
	v_rcp_f32_e32 v100, v99
	v_cndmask_b32_e32 v101, 0, v133, vcc
	s_waitcnt lgkmcnt(1)
; #define LAS __attribute__((address_space(3)))
; __device__ __forceinline__ f32x4 mfma16(bf16x8 a, bf16x8 b, f32x4 c) { return __builtin_amdgcn_mfma_f32_16x16x32_bf16(a, b, c, 0, 0, 0); }
; __device__ __forceinline__ void ret_phase(const Params& P, LAS unsigned char* lds, int tid, int lane, int wave, int bid, int G) {
;     ...
;         for (int t = 0; t < 8; ++t)
; #pragma unroll
;             for (int ks = 0; ks < 4; ++ks) { o[t] = mfma16(qf[ks], *(const LAS bf16x8*)(Qt + off256(16 * t + l15, 4 * ks + g)), o[t]); }
;         float wb[4];
; #pragma unroll
;         for (int i = 0; i < 4; ++i) { const float pos = (float)(w16 + 4 * g + i); const float wf = exp2f(lgf2 * (pos + 1.f)); wb[i] = exp2f(lgb2 * (128.f - pos)); const float rt = wf / wb[i];
; #pragma unroll
;             for (int t = 0; t < 8; ++t) o[t][i] *= rt; }
; #pragma unroll
;         for (int t = 0; t < 8; ++t)
; #pragma unroll
;             for (int ks = 0; ks < 4; ++ks) { o[t] = mfma16(qf[ks], *(const LAS bf16x8*)(Kt + off256(16 * t + l15, 4 * ks + g)), o[t]); }
	v_mfma_f32_16x16x32_bf16 v[94:97], v[50:53], v[94:97], v[66:69]
	v_ldexp_f32 v123, v98, v101
	v_fma_f32 v98, -v99, v100, 1.0
	v_fmac_f32_e32 v100, v98, v100
	v_div_scale_f32 v98, vcc, v119, v122, v119
	v_mul_f32_e32 v101, v98, v100
	v_fma_f32 v103, -v99, v101, v98
	v_fmac_f32_e32 v101, v103, v100
	v_fma_f32 v98, -v99, v101, v98
	v_div_scale_f32 v99, s[0:1], v123, v123, v124
	v_rcp_f32_e32 v103, v99
	v_div_fmas_f32 v98, v98, v100, v101
	v_div_fixup_f32 v98, v98, v122, v119
	v_mfma_f32_16x16x32_bf16 v[66:69], v[58:61], v[156:159], 0
	v_fma_f32 v100, -v99, v103, 1.0
	v_fmac_f32_e32 v103, v100, v103
	v_div_scale_f32 v100, vcc, v124, v123, v124
	v_mul_f32_e32 v101, v100, v103
	v_fma_f32 v119, -v99, v101, v100
	v_fmac_f32_e32 v101, v119, v103
	v_fma_f32 v99, -v99, v101, v100
	v_or_b32_e32 v100, 2, v102
	v_cvt_f32_i32_e32 v100, v100
	v_div_fmas_f32 v99, v99, v103, v101
	v_or_b32_e32 v102, 3, v102
	v_cvt_f32_i32_e32 v102, v102
	v_add_f32_e32 v101, 1.0, v100
	v_mul_f32_e32 v103, v105, v101
	v_cmp_gt_f32_e32 vcc, s52, v103
	v_sub_f32_e32 v100, 0x43000000, v100
	v_mul_f32_e32 v119, v104, v100
	v_cndmask_b32_e32 v103, 0, v132, vcc
	v_fmac_f32_e32 v103, v105, v101
	v_exp_f32_e32 v101, v103
	v_cndmask_b32_e32 v103, 0, v133, vcc
	v_cmp_gt_f32_e32 vcc, s52, v119
	v_div_fixup_f32 v99, v99, v123, v124
	v_mfma_f32_16x16x32_bf16 v[66:69], v[54:57], v[160:163], v[66:69]
	v_cndmask_b32_e32 v119, 0, v132, vcc
	v_fmac_f32_e32 v119, v104, v100
	v_exp_f32_e32 v100, v119
	v_add_f32_e32 v119, 1.0, v102
	v_mul_f32_e32 v124, v105, v119
	v_cmp_gt_f32_e64 s[0:1], s52, v124
	v_sub_f32_e32 v102, 0x43000000, v102
	v_mfma_f32_16x16x32_bf16 v[66:69], v[62:65], v[164:167], v[66:69]
	v_cndmask_b32_e64 v124, 0, v132, s[0:1]
	v_fmac_f32_e32 v124, v105, v119
	v_mul_f32_e32 v119, v104, v102
	v_cmp_gt_f32_e64 s[4:5], s52, v119
	v_exp_f32_e32 v105, v124
	ds_read_b128 v[136:139], v135 offset:36864
	v_cndmask_b32_e64 v119, 0, v132, s[4:5]
	v_fmac_f32_e32 v119, v104, v102
	v_exp_f32_e32 v102, v119
	v_cndmask_b32_e64 v104, 0, v133, s[0:1]
	v_ldexp_f32 v104, v105, v104
	v_cndmask_b32_e64 v105, 0, v133, s[4:5]
	v_ldexp_f32 v125, v102, v105
	v_div_scale_f32 v102, s[0:1], v125, v125, v104
	v_rcp_f32_e32 v105, v102
	v_ldexp_f32 v119, v101, v103
	v_cndmask_b32_e32 v101, 0, v133, vcc
	v_ldexp_f32 v124, v100, v101
	v_fma_f32 v100, -v102, v105, 1.0
	v_fmac_f32_e32 v105, v100, v105
	v_div_scale_f32 v100, vcc, v104, v125, v104
	v_mul_f32_e32 v101, v100, v105
	v_fma_f32 v103, -v102, v101, v100
	v_fmac_f32_e32 v101, v103, v105
	v_fma_f32 v100, -v102, v101, v100
	v_div_scale_f32 v102, s[0:1], v124, v124, v119
	v_rcp_f32_e32 v103, v102
	v_div_fmas_f32 v100, v100, v105, v101
	v_div_fixup_f32 v157, v100, v125, v104
	v_pk_mul_f32 v[74:75], v[98:99], v[74:75]
	v_fma_f32 v100, -v102, v103, 1.0
	v_fmac_f32_e32 v103, v100, v103
	v_div_scale_f32 v100, vcc, v119, v124, v119
	v_mul_f32_e32 v101, v100, v103
	v_fma_f32 v104, -v102, v101, v100
	v_fmac_f32_e32 v101, v104, v103
	v_fma_f32 v100, -v102, v101, v100
	v_div_fmas_f32 v104, v100, v103, v101
	ds_read_b128 v[100:103], v135 offset:32768
	v_div_fixup_f32 v156, v104, v124, v119
	v_pk_mul_f32 v[76:77], v[156:157], v[76:77]
	s_waitcnt lgkmcnt(2)
	v_mfma_f32_16x16x32_bf16 v[66:69], v[50:53], v[140:143], v[66:69]
	v_mul_f32_e64 v72, v156, v72
	v_mul_f32_e64 v73, v157, v73
	v_pk_mul_f32 v[70:71], v[98:99], v[70:71]
	v_pk_mul_f32 v[96:97], v[156:157], v[96:97]
	s_waitcnt lgkmcnt(0)
	v_mfma_f32_16x16x32_bf16 v[74:77], v[58:61], v[100:103], v[74:77]
	ds_read_b128 v[100:103], v168 offset:32768
	ds_read_b128 v[140:143], v168 offset:36864
	v_pk_mul_f32 v[94:95], v[98:99], v[94:95]
	s_add_u32 s0, s40, s46
	v_mfma_f32_16x16x32_bf16 v[70:73], v[58:61], v[136:139], v[70:73]
	s_addc_u32 s1, s41, 0
	v_ashrrev_i32_e32 v119, 31, v118
	s_lshl_b32 s18, s57, 8
	v_mfma_f32_16x16x32_bf16 v[86:89], v[62:65], v[144:147], v[86:89]
	v_mul_f32_e64 v68, v156, v68
	v_mul_f32_e64 v69, v157, v69
	v_pk_mul_f32 v[66:67], v[98:99], v[66:67]
	v_lshlrev_b32_e32 v152, 3, v1
	s_waitcnt lgkmcnt(1)
	v_mfma_f32_16x16x32_bf16 v[74:77], v[54:57], v[100:103], v[74:77]
	ds_read_b128 v[100:103], v169 offset:32768
	ds_read_b128 v[144:147], v169 offset:36864
	v_ashrrev_i32_e32 v153, 31, v152
	s_waitcnt lgkmcnt(2)
	v_mfma_f32_16x16x32_bf16 v[70:73], v[54:57], v[140:143], v[70:73]
	v_mfma_f32_16x16x32_bf16 v[86:89], v[50:53], v[148:151], v[86:89]
	s_waitcnt lgkmcnt(1)
	v_mfma_f32_16x16x32_bf16 v[74:77], v[62:65], v[100:103], v[74:77]
	ds_read_b128 v[100:103], v170 offset:32768
	ds_read_b128 v[148:151], v170 offset:36864
	ds_read_b128 v[136:139], v135 offset:40960
	ds_read_b128 v[140:143], v135 offset:45056
	s_waitcnt lgkmcnt(4)
	v_mfma_f32_16x16x32_bf16 v[70:73], v[62:65], v[144:147], v[70:73]
	s_waitcnt lgkmcnt(3)
	v_mfma_f32_16x16x32_bf16 v[102:105], v[50:53], v[100:103], v[74:77]
	v_lshl_add_u64 v[100:101], s[0:1], 0, v[118:119]
	s_add_u32 s0, s21, s18
	s_addc_u32 s1, s25, 0
	s_waitcnt lgkmcnt(2)
	v_mfma_f32_16x16x32_bf16 v[74:77], v[50:53], v[148:151], v[70:73]
	v_lshl_add_u64 v[158:159], v[152:153], 1, s[0:1]
	v_lshlrev_b64 v[100:101], 10, v[100:101]
	s_nop 0
	v_pk_mul_f32 v[104:105], v[124:125], v[104:105]
	v_pk_mul_f32 v[72:73], v[156:157], v[84:85]
	v_pk_mul_f32 v[70:71], v[98:99], v[82:83]
	v_pk_mul_f32 v[102:103], v[122:123], v[102:103]
	s_nop 0
	v_pk_mul_f32 v[76:77], v[124:125], v[76:77]
	s_waitcnt lgkmcnt(1)
	v_mfma_f32_16x16x32_bf16 v[70:73], v[58:61], v[136:139], v[70:73]
	ds_read_b128 v[82:85], v168 offset:40960
	ds_read_b128 v[136:139], v168 offset:45056
	v_pk_mul_f32 v[74:75], v[122:123], v[74:75]
	s_add_i32 s56, s56, s3
	s_waitcnt lgkmcnt(1)
; #define LAS __attribute__((address_space(3)))
; __device__ __forceinline__ s16x4 tr_read(const LAS unsigned char* p) { return __builtin_amdgcn_ds_read_tr16_b64_v4i16((LAS s16x4*)p); }
; __device__ __forceinline__ bf16x8 cat8(s16x4 a, s16x4 b) { return (bf16x8){a[0], a[1], a[2], a[3], b[0], b[1], b[2], b[3]}; }
; __device__ __forceinline__ f32x4 mfma16(bf16x8 a, bf16x8 b, f32x4 c) { return __builtin_amdgcn_mfma_f32_16x16x32_bf16(a, b, c, 0, 0, 0); }
; #define OPQ_ALL() do { asm volatile("" : "+v"(g), "+v"(l15), "+v"(q4), "+v"(p)); } while (0)
; __device__ __forceinline__ void ret_phase(const Params& P, LAS unsigned char* lds, int tid, int lane, int wave, int bid, int G) {
;     ...
;         u32x4 grv[4];
; #pragma unroll
;         for (int it = 0; it < 4; ++it) grv[it] = *(const u32x4*)(GR + (tokc + w16 + 4 * it + g) * 512 + h * 128 + 8 * l15);
; #pragma unroll
;         for (int t = 0; t < 8; ++t)
; #pragma unroll
;             for (int ks = 0; ks < 4; ++ks) { o[t] = mfma16(qf[ks], *(const LAS bf16x8*)(Qt + off256(16 * t + l15, 4 * ks + g)), o[t]); }
;         float wb[4];
; #pragma unroll
;         for (int i = 0; i < 4; ++i) { const float pos = (float)(w16 + 4 * g + i); const float wf = exp2f(lgf2 * (pos + 1.f)); wb[i] = exp2f(lgb2 * (128.f - pos)); const float rt = wf / wb[i];
; #pragma unroll
;             for (int t = 0; t < 8; ++t) o[t][i] *= rt; }
; #pragma unroll
;         for (int t = 0; t < 8; ++t)
; #pragma unroll
;             for (int ks = 0; ks < 4; ++ks) { o[t] = mfma16(qf[ks], *(const LAS bf16x8*)(Kt + off256(16 * t + l15, 4 * ks + g)), o[t]); }
; #pragma unroll
;         for (int i = 0; i < 4; ++i)
; #pragma unroll
;             for (int t = 0; t < 8; ++t) o[t][i] *= wb[i];
;         OPQ_ALL();
; #pragma unroll
;         for (int ks = 0; ks < 4; ++ks) {
;             const bf16x8 pa = *(const LAS bf16x8*)(Pt + off256(w16 + l15, 4 * ks + g));
;             const unsigned r0 = 32 * ks + 8 * g + q4, r1 = r0 + 4;
; #pragma unroll
;             for (int t = 0; t < 8; ++t) { const unsigned ch = 2 * t + (p >> 1);
;                 const bf16x8 vb = cat8(tr_read(Vt + off256(r0, ch) + 8 * (p & 1)), tr_read(Vt + off256(r1, ch) + 8 * (p & 1)));
;                 o[t] = mfma16(pa, vb, o[t]); }
	v_mfma_f32_16x16x32_bf16 v[70:73], v[54:57], v[82:85], v[70:73]
	ds_read_b128 v[82:85], v169 offset:40960
	ds_read_b128 v[144:147], v169 offset:45056
	s_waitcnt lgkmcnt(1)
	v_mfma_f32_16x16x32_bf16 v[70:73], v[62:65], v[82:85], v[70:73]
	ds_read_b128 v[82:85], v170 offset:40960
	ds_read_b128 v[148:151], v170 offset:45056
	s_waitcnt lgkmcnt(1)
	v_mfma_f32_16x16x32_bf16 v[82:85], v[50:53], v[82:85], v[70:73]
	s_nop 3
	v_mul_f32_e64 v72, v156, v80
	v_mul_f32_e64 v73, v157, v81
	v_pk_mul_f32 v[70:71], v[98:99], v[78:79]
	s_nop 0
	v_pk_mul_f32 v[84:85], v[124:125], v[84:85]
	v_pk_mul_f32 v[82:83], v[122:123], v[82:83]
	v_mfma_f32_16x16x32_bf16 v[70:73], v[58:61], v[140:143], v[70:73]
	ds_read_b128 v[140:143], v135 offset:53248
	v_mfma_f32_16x16x32_bf16 v[70:73], v[54:57], v[136:139], v[70:73]
	ds_read_b128 v[136:139], v135 offset:49152
	v_mfma_f32_16x16x32_bf16 v[70:73], v[62:65], v[144:147], v[70:73]
	s_waitcnt lgkmcnt(2)
	v_mfma_f32_16x16x32_bf16 v[78:81], v[50:53], v[148:151], v[70:73]
	s_nop 5
	v_mul_f32_e64 v72, v156, v92
	v_mul_f32_e64 v73, v157, v93
	v_pk_mul_f32 v[70:71], v[98:99], v[90:91]
	v_pk_mul_f32 v[80:81], v[124:125], v[80:81]
	v_pk_mul_f32 v[78:79], v[122:123], v[78:79]
	s_waitcnt lgkmcnt(0)
	v_mfma_f32_16x16x32_bf16 v[70:73], v[58:61], v[136:139], v[70:73]
	ds_read_b128 v[90:93], v168 offset:49152
	ds_read_b128 v[136:139], v168 offset:53248
	s_waitcnt lgkmcnt(1)
	v_mfma_f32_16x16x32_bf16 v[70:73], v[54:57], v[90:93], v[70:73]
	ds_read_b128 v[90:93], v169 offset:49152
	ds_read_b128 v[144:147], v169 offset:53248
	s_waitcnt lgkmcnt(1)
	v_mfma_f32_16x16x32_bf16 v[70:73], v[62:65], v[90:93], v[70:73]
	ds_read_b128 v[90:93], v170 offset:49152
	ds_read_b128 v[148:151], v170 offset:53248
	s_waitcnt lgkmcnt(1)
	v_mfma_f32_16x16x32_bf16 v[90:93], v[50:53], v[90:93], v[70:73]
	s_nop 3
	v_mul_f32_e64 v72, v156, v88
	v_mul_f32_e64 v73, v157, v89
	v_pk_mul_f32 v[70:71], v[98:99], v[86:87]
	s_nop 0
	v_pk_mul_f32 v[92:93], v[124:125], v[92:93]
	v_pk_mul_f32 v[90:91], v[122:123], v[90:91]
	v_mfma_f32_16x16x32_bf16 v[70:73], v[58:61], v[140:143], v[70:73]
	v_mfma_f32_16x16x32_bf16 v[70:73], v[54:57], v[136:139], v[70:73]
	v_mfma_f32_16x16x32_bf16 v[70:73], v[62:65], v[144:147], v[70:73]
	s_waitcnt lgkmcnt(0)
	v_mfma_f32_16x16x32_bf16 v[86:89], v[50:53], v[148:151], v[70:73]
	s_nop 5
	ds_read_b128 v[70:73], v135 offset:57344
	ds_read_b128 v[136:139], v168 offset:57344
	ds_read_b128 v[140:143], v135 offset:61440
	s_waitcnt lgkmcnt(2)
	v_mfma_f32_16x16x32_bf16 v[70:73], v[58:61], v[70:73], v[94:97]
	s_nop 2
	ds_read_b128 v[94:97], v169 offset:57344
	ds_read_b128 v[144:147], v168 offset:61440
	v_pk_mul_f32 v[88:89], v[124:125], v[88:89]
	v_pk_mul_f32 v[86:87], v[122:123], v[86:87]
	s_waitcnt lgkmcnt(3)
	v_mfma_f32_16x16x32_bf16 v[70:73], v[54:57], v[136:139], v[70:73]
	ds_read_b128 v[136:139], v170 offset:57344
	ds_read_b128 v[148:151], v169 offset:61440
	ds_read_b128 v[152:155], v170 offset:61440
	s_waitcnt lgkmcnt(4)
	v_mfma_f32_16x16x32_bf16 v[70:73], v[62:65], v[94:97], v[70:73]
	s_waitcnt lgkmcnt(2)
	v_mfma_f32_16x16x32_bf16 v[94:97], v[50:53], v[136:139], v[70:73]
	v_lshl_add_u64 v[136:137], v[158:159], 0, v[100:101]
	v_mfma_f32_16x16x32_bf16 v[70:73], v[58:61], v[140:143], v[66:69]
	v_add_co_u32_e32 v58, vcc, s49, v136
	s_nop 4
	v_pk_mul_f32 v[96:97], v[124:125], v[96:97]
	v_mfma_f32_16x16x32_bf16 v[98:101], v[54:57], v[144:147], v[70:73]
	v_addc_co_u32_e32 v59, vcc, 0, v137, vcc
	v_add_co_u32_e32 v54, vcc, s53, v136
	global_load_dwordx4 v[66:69], v[58:59], off offset:-4096
	s_nop 0
	global_load_dwordx4 v[58:61], v[58:59], off
	v_addc_co_u32_e32 v55, vcc, 0, v137, vcc
	global_load_dwordx4 v[70:73], v[136:137], off
	s_nop 0
	global_load_dwordx4 v[54:57], v[54:55], off
	s_waitcnt lgkmcnt(1)
	v_mfma_f32_16x16x32_bf16 v[142:145], v[62:65], v[148:151], v[98:101]
	v_mul_f32_e64 v94, v122, v94
	v_mul_f32_e64 v95, v123, v95
	v_add_u32_e32 v62, s46, v1
	v_lshl_add_u32 v139, v62, 8, s51
	v_lshlrev_b32_e32 v62, 2, v113
	v_lshl_add_u32 v137, v118, 3, v113
	v_and_b32_e32 v119, 12, v62
	v_lshlrev_b32_e32 v62, 3, v126
	v_lshlrev_b32_e32 v63, 2, v1
	v_and_b32_e32 v62, 8, v62
	v_add_u32_e32 v64, 4, v137
	v_and_b32_e32 v136, 12, v63
	v_bfe_u32 v138, v1, 2, 2
	v_ashrrev_i32_e32 v135, 1, v126
	v_add_u32_e32 v140, s48, v62
	v_bfe_u32 v151, v64, 2, 2
	v_bfe_u32 v141, v137, 2, 2
	v_bitop3_b32 v63, v136, v118, v138 bitop3:0x36
	v_lshl_add_u32 v156, v64, 8, v140
	v_bitop3_b32 v100, v151, v135, v119 bitop3:0x36
	v_bitop3_b32 v62, v141, v135, v119 bitop3:0x36
	v_lshl_add_u32 v63, v63, 4, v139
	v_lshl_add_u32 v150, v137, 8, v140
	v_lshl_add_u32 v100, v100, 4, v156
	v_lshl_add_u32 v157, v62, 4, v150
	ds_read_b128 v[62:65], v63
	ds_read_b64_tr_b16 v[98:99], v157
	ds_read_b64_tr_b16 v[100:101], v100
	v_add_u32_e32 v170, 2, v135
	s_waitcnt lgkmcnt(3)
	v_mfma_f32_16x16x32_bf16 v[50:53], v[50:53], v[152:155], v[142:145]
	v_add_u32_e32 v171, 4, v135
	v_add_u32_e32 v200, 6, v135
	v_add_u32_e32 v201, 8, v135
	ds_read_b64_tr_b16 v[142:143], v157 offset:24576
	s_waitcnt lgkmcnt(1)
	v_mfma_f32_16x16x32_bf16 v[98:101], v[62:65], v[98:101], v[102:105]
	v_add_u32_e32 v202, 10, v135
	v_add_u32_e32 v203, 12, v135
	v_add_u32_e32 v204, 14, v135
	v_bitop3_b32 v102, v141, v170, v119 bitop3:0x36
	v_lshl_add_u32 v146, v102, 4, v150
	ds_read_b64_tr_b16 v[102:103], v146
	v_bitop3_b32 v104, v151, v170, v119 bitop3:0x36
	v_lshl_add_u32 v104, v104, 4, v156
	v_bitop3_b32 v105, v141, v171, v119 bitop3:0x36
	v_lshl_add_u32 v160, v105, 4, v150
	ds_read_b64_tr_b16 v[104:105], v104
	ds_read_b64_tr_b16 v[144:145], v160
	ds_read_b64_tr_b16 v[148:149], v160 offset:8192
	ds_read_b64_tr_b16 v[152:153], v160 offset:16384
	ds_read_b64_tr_b16 v[154:155], v146 offset:8192
	ds_read_b64_tr_b16 v[158:159], v146 offset:16384
	ds_read_b64_tr_b16 v[162:163], v146 offset:24576
	s_waitcnt lgkmcnt(6)
; #define LAS __attribute__((address_space(3)))
; __device__ __forceinline__ s16x4 tr_read(const LAS unsigned char* p) { return __builtin_amdgcn_ds_read_tr16_b64_v4i16((LAS s16x4*)p); }
; __device__ __forceinline__ bf16x8 cat8(s16x4 a, s16x4 b) { return (bf16x8){a[0], a[1], a[2], a[3], b[0], b[1], b[2], b[3]}; }
; __device__ __forceinline__ f32x4 mfma16(bf16x8 a, bf16x8 b, f32x4 c) { return __builtin_amdgcn_mfma_f32_16x16x32_bf16(a, b, c, 0, 0, 0); }
; __device__ __forceinline__ void ret_phase(const Params& P, LAS unsigned char* lds, int tid, int lane, int wave, int bid, int G) {
;     ...
; #pragma unroll
;         for (int ks = 0; ks < 4; ++ks) {
;             const bf16x8 pa = *(const LAS bf16x8*)(Pt + off256(w16 + l15, 4 * ks + g));
;             const unsigned r0 = 32 * ks + 8 * g + q4, r1 = r0 + 4;
; #pragma unroll
;             for (int t = 0; t < 8; ++t) { const unsigned ch = 2 * t + (p >> 1);
;                 const bf16x8 vb = cat8(tr_read(Vt + off256(r0, ch) + 8 * (p & 1)), tr_read(Vt + off256(r1, ch) + 8 * (p & 1)));
;                 o[t] = mfma16(pa, vb, o[t]); }
;         }
	v_mfma_f32_16x16x32_bf16 v[74:77], v[62:65], v[102:105], v[74:77]
	v_bitop3_b32 v102, v151, v171, v119 bitop3:0x36
	v_lshl_add_u32 v102, v102, 4, v156
	ds_read_b64_tr_b16 v[146:147], v102
	v_bitop3_b32 v102, v141, v200, v119 bitop3:0x36
	v_bitop3_b32 v104, v151, v200, v119 bitop3:0x36
	v_lshl_add_u32 v190, v102, 4, v150
	v_lshl_add_u32 v104, v104, 4, v156
	ds_read_b64_tr_b16 v[102:103], v190
	ds_read_b64_tr_b16 v[164:165], v190 offset:8192
	ds_read_b64_tr_b16 v[168:169], v160 offset:24576
	s_waitcnt lgkmcnt(3)
	v_mfma_f32_16x16x32_bf16 v[82:85], v[62:65], v[144:147], v[82:85]
	ds_read_b64_tr_b16 v[104:105], v104
	v_bitop3_b32 v144, v141, v201, v119 bitop3:0x36
	v_lshl_add_u32 v160, v144, 4, v150
	v_bitop3_b32 v144, v151, v201, v119 bitop3:0x36
	v_lshl_add_u32 v144, v144, 4, v156
	ds_read_b64_tr_b16 v[146:147], v144
	ds_read_b64_tr_b16 v[144:145], v160
	ds_read_b64_tr_b16 v[172:173], v190 offset:24576
	s_waitcnt lgkmcnt(3)
	v_mfma_f32_16x16x32_bf16 v[78:81], v[62:65], v[102:105], v[78:81]
	v_bitop3_b32 v104, v141, v202, v119 bitop3:0x36
	v_lshl_add_u32 v104, v104, 4, v150
	v_bitop3_b32 v105, v151, v202, v119 bitop3:0x36
	ds_read_b64_tr_b16 v[102:103], v160 offset:24576
	s_waitcnt lgkmcnt(2)
	v_mfma_f32_16x16x32_bf16 v[90:93], v[62:65], v[144:147], v[90:93]
	ds_read_b64_tr_b16 v[144:145], v104
	v_lshl_add_u32 v105, v105, 4, v156
	v_bitop3_b32 v146, v141, v203, v119 bitop3:0x36
	v_lshl_add_u32 v161, v146, 4, v150
	ds_read_b64_tr_b16 v[146:147], v105
	ds_read_b64_tr_b16 v[174:175], v161
	ds_read_b64_tr_b16 v[178:179], v161 offset:8192
	ds_read_b64_tr_b16 v[182:183], v161 offset:16384
	ds_read_b64_tr_b16 v[184:185], v104 offset:8192
	ds_read_b64_tr_b16 v[188:189], v104 offset:16384
	ds_read_b64_tr_b16 v[192:193], v104 offset:24576
	v_bitop3_b32 v104, v151, v203, v119 bitop3:0x36
	v_lshl_add_u32 v104, v104, 4, v156
	ds_read_b64_tr_b16 v[176:177], v104
	v_bitop3_b32 v105, v151, v204, v119 bitop3:0x36
	v_bitop3_b32 v104, v141, v204, v119 bitop3:0x36
	v_lshl_add_u32 v105, v105, 4, v156
	s_waitcnt lgkmcnt(7)
	v_mfma_f32_16x16x32_bf16 v[86:89], v[62:65], v[144:147], v[86:89]
	v_lshl_add_u32 v104, v104, 4, v150
	ds_read_b64_tr_b16 v[146:147], v105
	ds_read_b64_tr_b16 v[144:145], v104
	ds_read_b64_tr_b16 v[194:195], v104 offset:8192
	ds_read_b64_tr_b16 v[198:199], v161 offset:24576
	v_pk_mul_f32 v[52:53], v[124:125], v[52:53]
	v_pk_mul_f32 v[50:51], v[122:123], v[50:51]
	s_waitcnt lgkmcnt(4)
	v_mfma_f32_16x16x32_bf16 v[94:97], v[62:65], v[174:177], v[94:97]
	ds_read_b64_tr_b16 v[122:123], v104 offset:24576
	v_add_u32_e32 v105, 36, v137
	v_bfe_u32 v124, v105, 2, 2
	s_waitcnt lgkmcnt(3)
	v_mfma_f32_16x16x32_bf16 v[50:53], v[62:65], v[144:147], v[50:53]
	v_add_u32_e32 v62, 4, v118
	v_bitop3_b32 v62, v136, v62, v138 bitop3:0x36
	v_lshl_add_u32 v62, v62, 4, v139
	ds_read_b128 v[62:65], v62
	v_lshl_add_u32 v105, v105, 8, v140
	v_bitop3_b32 v125, v124, v135, v119 bitop3:0x36
	v_lshl_add_u32 v125, v125, 4, v105
	ds_read_b64_tr_b16 v[146:147], v125
	ds_read_b64_tr_b16 v[144:145], v157 offset:8192
	ds_read_b64_tr_b16 v[174:175], v157 offset:16384
	v_bitop3_b32 v125, v124, v170, v119 bitop3:0x36
	v_lshl_add_u32 v125, v125, 4, v105
	ds_read_b64_tr_b16 v[156:157], v125
	v_bitop3_b32 v125, v124, v171, v119 bitop3:0x36
	s_waitcnt lgkmcnt(2)
	v_mfma_f32_16x16x32_bf16 v[98:101], v[62:65], v[144:147], v[98:101]
	v_lshl_add_u32 v125, v125, 4, v105
	v_bitop3_b32 v141, v124, v200, v119 bitop3:0x36
	v_bitop3_b32 v144, v124, v201, v119 bitop3:0x36
	v_lshl_add_u32 v141, v141, 4, v105
	v_lshl_add_u32 v144, v144, 4, v105
	ds_read_b64_tr_b16 v[150:151], v125
	ds_read_b64_tr_b16 v[166:167], v141
	ds_read_b64_tr_b16 v[146:147], v144
	v_bitop3_b32 v125, v124, v202, v119 bitop3:0x36
	v_lshl_add_u32 v125, v125, 4, v105
	s_waitcnt lgkmcnt(2)
	v_mfma_f32_16x16x32_bf16 v[82:85], v[62:65], v[148:151], v[82:85]
	ds_read_b64_tr_b16 v[144:145], v160 offset:8192
	ds_read_b64_tr_b16 v[148:149], v160 offset:16384
	ds_read_b64_tr_b16 v[186:187], v125
	v_bitop3_b32 v125, v124, v203, v119 bitop3:0x36
	v_lshl_add_u32 v125, v125, 4, v105
	v_bitop3_b32 v124, v124, v204, v119 bitop3:0x36
	v_lshl_add_u32 v105, v124, 4, v105
	ds_read_b64_tr_b16 v[180:181], v125
	ds_read_b64_tr_b16 v[196:197], v105
	v_add_u32_e32 v105, 0x44, v137
	v_mfma_f32_16x16x32_bf16 v[74:77], v[62:65], v[154:157], v[74:77]
	v_bfe_u32 v124, v105, 2, 2
	v_lshl_add_u32 v105, v105, 8, v140
	v_bitop3_b32 v125, v124, v135, v119 bitop3:0x36
	s_waitcnt lgkmcnt(6)
	v_mfma_f32_16x16x32_bf16 v[78:81], v[62:65], v[164:167], v[78:81]
	v_lshl_add_u32 v125, v125, 4, v105
	ds_read_b64_tr_b16 v[176:177], v125
	v_bitop3_b32 v125, v124, v170, v119 bitop3:0x36
	s_waitcnt lgkmcnt(5)
	v_mfma_f32_16x16x32_bf16 v[90:93], v[62:65], v[144:147], v[90:93]
	v_lshl_add_u32 v125, v125, 4, v105
	ds_read_b64_tr_b16 v[160:161], v125
	v_bitop3_b32 v125, v124, v171, v119 bitop3:0x36
	s_waitcnt lgkmcnt(4)
	v_mfma_f32_16x16x32_bf16 v[86:89], v[62:65], v[184:187], v[86:89]
	v_bitop3_b32 v144, v124, v201, v119 bitop3:0x36
	v_lshl_add_u32 v125, v125, 4, v105
	v_bitop3_b32 v141, v124, v200, v119 bitop3:0x36
	s_waitcnt lgkmcnt(3)
	v_mfma_f32_16x16x32_bf16 v[94:97], v[62:65], v[178:181], v[94:97]
	v_lshl_add_u32 v144, v144, 4, v105
	v_lshl_add_u32 v141, v141, 4, v105
	s_waitcnt lgkmcnt(2)
	v_mfma_f32_16x16x32_bf16 v[50:53], v[62:65], v[194:197], v[50:53]
	v_add_u32_e32 v62, 8, v118
	v_bitop3_b32 v62, v136, v62, v138 bitop3:0x36
	v_lshl_add_u32 v62, v62, 4, v139
	ds_read_b128 v[62:65], v62
	ds_read_b64_tr_b16 v[154:155], v125
	ds_read_b64_tr_b16 v[146:147], v141
	ds_read_b64_tr_b16 v[150:151], v144
	ds_read_b64_tr_b16 v[144:145], v190 offset:16384
	s_waitcnt lgkmcnt(0)
; #define LAS __attribute__((address_space(3)))
; __device__ __forceinline__ s16x4 tr_read(const LAS unsigned char* p) { return __builtin_amdgcn_ds_read_tr16_b64_v4i16((LAS s16x4*)p); }
; __device__ __forceinline__ bf16x8 cat8(s16x4 a, s16x4 b) { return (bf16x8){a[0], a[1], a[2], a[3], b[0], b[1], b[2], b[3]}; }
; __device__ __forceinline__ f32x4 mfma16(bf16x8 a, bf16x8 b, f32x4 c) { return __builtin_amdgcn_mfma_f32_16x16x32_bf16(a, b, c, 0, 0, 0); }
; #define LBAR() asm volatile("s_waitcnt lgkmcnt(0)\n\ts_barrier" ::: "memory")
; #define OPQ_ALL() do { asm volatile("" : "+v"(g), "+v"(l15), "+v"(q4), "+v"(p)); } while (0)
; __device__ __forceinline__ void ret_phase(const Params& P, LAS unsigned char* lds, int tid, int lane, int wave, int bid, int G) {
;     ...
; #pragma unroll
;         for (int ks = 0; ks < 4; ++ks) {
;             const bf16x8 pa = *(const LAS bf16x8*)(Pt + off256(w16 + l15, 4 * ks + g));
;             const unsigned r0 = 32 * ks + 8 * g + q4, r1 = r0 + 4;
; #pragma unroll
;             for (int t = 0; t < 8; ++t) { const unsigned ch = 2 * t + (p >> 1);
;                 const bf16x8 vb = cat8(tr_read(Vt + off256(r0, ch) + 8 * (p & 1)), tr_read(Vt + off256(r1, ch) + 8 * (p & 1)));
;                 o[t] = mfma16(pa, vb, o[t]); }
;         }
;         OPQ_ALL();
;         float rs[4];
; #pragma unroll
;         for (int i = 0; i < 4; ++i) { float ss = 0.f;
; #pragma unroll
;             for (int t = 0; t < 8; ++t) ss += o[t][i] * o[t][i];
;             ss += __shfl_xor(ss, 1); ss += __shfl_xor(ss, 2); ss += __shfl_xor(ss, 4); ss += __shfl_xor(ss, 8);
;             rs[i] = rsqrtf(ss * (1.f / 128.f) + EPS); }
;         LBAR();
	v_mfma_f32_16x16x32_bf16 v[78:81], v[62:65], v[144:147], v[78:81]
	v_mfma_f32_16x16x32_bf16 v[146:149], v[62:65], v[148:151], v[90:93]
	s_nop 2
	v_bitop3_b32 v90, v124, v202, v119 bitop3:0x36
	v_lshl_add_u32 v90, v90, 4, v105
	ds_read_b64_tr_b16 v[190:191], v90
	v_bitop3_b32 v90, v124, v203, v119 bitop3:0x36
	v_bitop3_b32 v91, v124, v204, v119 bitop3:0x36
	v_lshl_add_u32 v90, v90, 4, v105
	v_lshl_add_u32 v91, v91, 4, v105
	v_mfma_f32_16x16x32_bf16 v[82:85], v[62:65], v[152:155], v[82:85]
	ds_read_b64_tr_b16 v[184:185], v90
	ds_read_b64_tr_b16 v[90:91], v91
	s_waitcnt lgkmcnt(2)
	v_mfma_f32_16x16x32_bf16 v[150:153], v[62:65], v[188:191], v[86:89]
	s_nop 2
	ds_read_b64_tr_b16 v[88:89], v104 offset:16384
	v_mfma_f32_16x16x32_bf16 v[98:101], v[62:65], v[174:177], v[98:101]
	v_mfma_f32_16x16x32_bf16 v[74:77], v[62:65], v[158:161], v[74:77]
	s_waitcnt lgkmcnt(2)
	v_mfma_f32_16x16x32_bf16 v[154:157], v[62:65], v[182:185], v[94:97]
	s_waitcnt lgkmcnt(0)
	v_mfma_f32_16x16x32_bf16 v[50:53], v[62:65], v[88:91], v[50:53]
	v_add_u32_e32 v62, 12, v118
	v_bitop3_b32 v62, v136, v62, v138 bitop3:0x36
	v_lshl_add_u32 v62, v62, 4, v139
	ds_read_b128 v[158:161], v62
	v_add_u32_e32 v62, 0x64, v137
	v_bfe_u32 v63, v62, 2, 2
	v_lshl_add_u32 v62, v62, 8, v140
	v_bitop3_b32 v64, v63, v135, v119 bitop3:0x36
	v_lshl_add_u32 v64, v64, 4, v62
	ds_read_b64_tr_b16 v[144:145], v64
	v_bitop3_b32 v64, v63, v170, v119 bitop3:0x36
	v_lshl_add_u32 v64, v64, 4, v62
	ds_read_b64_tr_b16 v[164:165], v64
	v_bitop3_b32 v64, v63, v171, v119 bitop3:0x36
	v_lshl_add_u32 v64, v64, 4, v62
	v_bitop3_b32 v65, v63, v200, v119 bitop3:0x36
	v_bitop3_b32 v86, v63, v201, v119 bitop3:0x36
	v_lshl_add_u32 v65, v65, 4, v62
	v_lshl_add_u32 v86, v86, 4, v62
	ds_read_b64_tr_b16 v[170:171], v64
	ds_read_b64_tr_b16 v[174:175], v65
	ds_read_b64_tr_b16 v[104:105], v86
	v_bitop3_b32 v64, v63, v202, v119 bitop3:0x36
	v_lshl_add_u32 v64, v64, 4, v62
	ds_read_b64_tr_b16 v[194:195], v64
	v_bitop3_b32 v64, v63, v203, v119 bitop3:0x36
	v_lshl_add_u32 v64, v64, 4, v62
	v_bitop3_b32 v63, v63, v204, v119 bitop3:0x36
	v_lshl_add_u32 v62, v63, 4, v62
	ds_read_b64_tr_b16 v[200:201], v64
	ds_read_b64_tr_b16 v[124:125], v62
	s_waitcnt lgkmcnt(7)
	v_mfma_f32_16x16x32_bf16 v[94:97], v[158:161], v[142:145], v[98:101]
	v_xor_b32_e32 v140, 2, v134
	s_waitcnt lgkmcnt(0)
	s_barrier
	s_waitcnt lgkmcnt(5)
	v_mfma_f32_16x16x32_bf16 v[86:89], v[158:161], v[168:171], v[82:85]
	v_and_b32_e32 v99, 64, v134
	v_xor_b32_e32 v98, 1, v134
	s_waitcnt lgkmcnt(4)
	v_mfma_f32_16x16x32_bf16 v[82:85], v[158:161], v[172:175], v[78:81]
	v_add_u32_e32 v119, 64, v99
	v_cmp_lt_i32_e32 vcc, v98, v119
	v_mfma_f32_16x16x32_bf16 v[90:93], v[158:161], v[162:165], v[74:77]
	s_nop 0
	v_cndmask_b32_e32 v98, v134, v98, vcc
	v_lshlrev_b32_e32 v135, 2, v98
	v_mov_b32_e32 v98, v86
	s_waitcnt lgkmcnt(3)
	v_mfma_f32_16x16x32_bf16 v[78:81], v[158:161], v[102:105], v[146:149]
	v_mov_b32_e32 v99, v82
	v_mov_b32_e32 v104, v87
	v_mov_b32_e32 v105, v83
	s_waitcnt lgkmcnt(2)
	v_mfma_f32_16x16x32_bf16 v[74:77], v[158:161], v[192:195], v[150:153]
	v_mul_f32_e64 v98, v98, v98
	v_mul_f32_e64 v99, v99, v99
	v_pk_mul_f32 v[104:105], v[104:105], v[104:105]
	v_mov_b32_e32 v100, v78
	s_waitcnt lgkmcnt(1)
	v_mfma_f32_16x16x32_bf16 v[62:65], v[158:161], v[198:201], v[154:157]
	v_mov_b32_e32 v138, v104
	s_nop 0
	v_mov_b32_e32 v101, v74
	v_mov_b32_e32 v139, v98
	s_waitcnt lgkmcnt(0)
	v_mfma_f32_16x16x32_bf16 v[50:53], v[158:161], v[122:125], v[50:53]
	v_mul_f32_e64 v122, v90, v90
	v_mul_f32_e64 v123, v91, v91
	v_mov_b32_e32 v124, v79
	v_pk_fma_f32 v[122:123], v[94:95], v[94:95], v[122:123]
	v_mov_b32_e32 v125, v75
	v_pk_mul_f32 v[100:101], v[100:101], v[100:101]
	v_pk_mul_f32 v[124:125], v[124:125], v[124:125]
	v_pk_add_f32 v[122:123], v[122:123], v[138:139] op_sel:[1,0] op_sel_hi:[0,1]
	v_mov_b32_e32 v98, v105
	v_mov_b32_e32 v102, v62
	v_mov_b32_e32 v103, v50
	v_mov_b32_e32 v136, v63
	v_mov_b32_e32 v137, v51
	v_pk_add_f32 v[98:99], v[122:123], v[98:99]
	v_mov_b32_e32 v104, v124
	v_mov_b32_e32 v105, v100
	v_pk_mul_f32 v[102:103], v[102:103], v[102:103]
	v_pk_mul_f32 v[136:137], v[136:137], v[136:137]
	v_pk_add_f32 v[98:99], v[98:99], v[104:105]
	v_mov_b32_e32 v100, v125
	v_pk_add_f32 v[98:99], v[98:99], v[100:101]
	v_mov_b32_e32 v100, v136
	v_mov_b32_e32 v101, v102
	v_pk_add_f32 v[98:99], v[98:99], v[100:101]
	v_mov_b32_e32 v102, v137
	v_pk_add_f32 v[98:99], v[98:99], v[102:103]
	s_nop 1
	v_mov_b32_dpp v101, v99 quad_perm:[1,0,3,2] row_mask:0xf bank_mask:0xf
	v_mov_b32_dpp v100, v98 quad_perm:[1,0,3,2] row_mask:0xf bank_mask:0xf
	v_cmp_lt_i32_e32 vcc, v140, v119
	v_mov_b32_e32 v122, v88
	v_mov_b32_e32 v123, v84
	v_cndmask_b32_e32 v102, v134, v140, vcc
	v_lshlrev_b32_e32 v146, 2, v102
	s_waitcnt lgkmcnt(0)
	v_pk_add_f32 v[98:99], v[98:99], v[100:101]
	s_nop 1
	v_mov_b32_dpp v101, v99 quad_perm:[2,3,0,1] row_mask:0xf bank_mask:0xf
	v_mov_b32_dpp v100, v98 quad_perm:[2,3,0,1] row_mask:0xf bank_mask:0xf
	v_xor_b32_e32 v102, 4, v134
	v_cmp_lt_i32_e32 vcc, v102, v119
	v_mov_b32_e32 v138, v89
	v_mov_b32_e32 v139, v85
	v_cndmask_b32_e32 v102, v134, v102, vcc
	v_lshlrev_b32_e32 v147, 2, v102
	s_waitcnt lgkmcnt(0)
	v_pk_add_f32 v[98:99], v[98:99], v[100:101]
	s_nop 1
	v_mov_b32_dpp v101, v99 row_half_mirror row_mask:0xf bank_mask:0xf
	v_mov_b32_dpp v100, v98 row_half_mirror row_mask:0xf bank_mask:0xf
	v_xor_b32_e32 v102, 8, v134
	v_cmp_lt_i32_e32 vcc, v102, v119
	v_pk_mul_f32 v[122:123], v[122:123], v[122:123]
	v_pk_mul_f32 v[138:139], v[138:139], v[138:139]
	s_waitcnt lgkmcnt(0)
; __device__ __forceinline__ unsigned cvt_pk_bf16(float lo, float hi) { unsigned r; asm volatile("v_cvt_pk_bf16_f32 %0, %1, %2" : "=v"(r) : "v"(lo), "v"(hi)); return r; }
; #define LAS __attribute__((address_space(3)))
; #define LBAR() asm volatile("s_waitcnt lgkmcnt(0)\n\ts_barrier" ::: "memory")
; __device__ __forceinline__ void ret_phase(const Params& P, LAS unsigned char* lds, int tid, int lane, int wave, int bid, int G) {
;     ...
;         float rs[4];
; #pragma unroll
;         for (int i = 0; i < 4; ++i) { float ss = 0.f;
; #pragma unroll
;             for (int t = 0; t < 8; ++t) ss += o[t][i] * o[t][i];
;             ss += __shfl_xor(ss, 1); ss += __shfl_xor(ss, 2); ss += __shfl_xor(ss, 4); ss += __shfl_xor(ss, 8);
;             rs[i] = rsqrtf(ss * (1.f / 128.f) + EPS); }
;         LBAR();
; #pragma unroll
;         for (int t = 0; t < 8; ++t) { const int dv = 16 * t + l15; const float gn = P.rgain[h * 128 + dv];
; #pragma unroll
;             for (int i = 0; i < 4; ++i) { const int n = w16 + 4 * g + i; const unsigned wv = cvt_pk_bf16(o[t][i] * rs[i] * gn, 0.f);
;                 *(LAS unsigned short*)(Pt + off256(n, dv >> 3) + 2 * (dv & 7)) = (unsigned short)(wv & 0xffffu); } }
	v_pk_add_f32 v[100:101], v[98:99], v[100:101]
	v_lshl_add_u32 v98, s57, 7, v1
	v_ashrrev_i32_e32 v99, 31, v98
	v_lshl_add_u64 v[98:99], v[98:99], 2, s[62:63]
	v_mov_b32_e32 v148, v205
	v_cndmask_b32_e32 v102, v134, v102, vcc
	v_lshlrev_b32_e32 v119, 2, v102
	v_pk_mul_f32 v[102:103], v[92:93], v[92:93]
	v_mov_b32_e32 v124, v80
	v_pk_fma_f32 v[102:103], v[96:97], v[96:97], v[102:103]
	v_mov_b32_e32 v125, v76
	v_mov_b32_e32 v140, v81
	v_mov_b32_e32 v141, v77
	v_mov_b32_e32 v144, v138
	v_mov_b32_e32 v145, v122
	v_pk_mul_f32 v[124:125], v[124:125], v[124:125]
	v_pk_mul_f32 v[140:141], v[140:141], v[140:141]
	v_pk_add_f32 v[102:103], v[102:103], v[144:145] op_sel:[1,0] op_sel_hi:[0,1]
	v_mov_b32_e32 v122, v139
	v_mov_b32_e32 v136, v64
	v_mov_b32_e32 v137, v52
	v_mov_b32_e32 v142, v65
	v_mov_b32_e32 v143, v53
	v_pk_add_f32 v[102:103], v[102:103], v[122:123]
	v_mov_b32_e32 v122, v140
	v_mov_b32_e32 v123, v124
	v_pk_mul_f32 v[136:137], v[136:137], v[136:137]
	v_pk_mul_f32 v[142:143], v[142:143], v[142:143]
	v_pk_add_f32 v[102:103], v[102:103], v[122:123]
	v_mov_b32_e32 v124, v141
	v_pk_add_f32 v[102:103], v[102:103], v[124:125]
	v_mov_b32_e32 v122, v142
	v_mov_b32_e32 v123, v136
	v_pk_add_f32 v[102:103], v[102:103], v[122:123]
	v_mov_b32_e32 v136, v143
	v_pk_add_f32 v[102:103], v[102:103], v[136:137]
	s_nop 1
	v_mov_b32_dpp v123, v103 quad_perm:[1,0,3,2] row_mask:0xf bank_mask:0xf
	v_mov_b32_dpp v122, v102 quad_perm:[1,0,3,2] row_mask:0xf bank_mask:0xf
	v_mov_b32_dpp v105, v101 row_mirror row_mask:0xf bank_mask:0xf
	v_mov_b32_dpp v104, v100 row_mirror row_mask:0xf bank_mask:0xf
	s_waitcnt lgkmcnt(2)
	v_pk_add_f32 v[102:103], v[102:103], v[122:123]
	s_nop 1
	v_mov_b32_dpp v123, v103 quad_perm:[2,3,0,1] row_mask:0xf bank_mask:0xf
	v_mov_b32_dpp v122, v102 quad_perm:[2,3,0,1] row_mask:0xf bank_mask:0xf
	s_waitcnt lgkmcnt(2)
	v_pk_add_f32 v[100:101], v[100:101], v[104:105]
	v_mov_b64_e32 v[104:105], s[24:25]
	v_pk_fma_f32 v[100:101], v[100:101], s[20:21], v[104:105] op_sel_hi:[1,0,0]
	s_waitcnt lgkmcnt(0)
	v_pk_add_f32 v[102:103], v[102:103], v[122:123]
	s_nop 1
	v_mov_b32_dpp v123, v103 row_half_mirror row_mask:0xf bank_mask:0xf
	v_mov_b32_dpp v122, v102 row_half_mirror row_mask:0xf bank_mask:0xf
	v_mul_f32_e32 v124, 0x4b800000, v101
	v_cmp_gt_f32_e32 vcc, s54, v101
	v_cmp_gt_f32_e64 s[0:1], s54, v100
	s_nop 0
	v_cndmask_b32_e32 v101, v101, v124, vcc
	v_rsq_f32_e32 v124, v101
	v_mul_f32_e32 v101, 0x4b800000, v100
	v_cndmask_b32_e64 v100, v100, v101, s[0:1]
	v_rsq_f32_e32 v125, v100
	s_waitcnt lgkmcnt(0)
	v_pk_add_f32 v[100:101], v[102:103], v[122:123]
	s_nop 1
	v_mov_b32_dpp v103, v101 row_mirror row_mask:0xf bank_mask:0xf
	v_mov_b32_dpp v102, v100 row_mirror row_mask:0xf bank_mask:0xf
	v_mul_f32_e32 v119, 0x45800000, v124
	v_cndmask_b32_e32 v119, v124, v119, vcc
	v_mul_f32_e32 v122, 0x45800000, v125
	v_mul_f32_e32 v94, v94, v119
	s_waitcnt lgkmcnt(0)
	v_pk_add_f32 v[100:101], v[100:101], v[102:103]
	v_mul_f32_e32 v90, v90, v119
	v_pk_fma_f32 v[100:101], v[100:101], s[20:21], v[104:105] op_sel_hi:[1,0,0]
	v_lshlrev_b32_e32 v105, 1, v1
	v_mul_f32_e32 v102, 0x4b800000, v101
	v_cmp_gt_f32_e32 vcc, s54, v101
	v_cmp_gt_f32_e64 s[4:5], s54, v100
	v_and_b32_e32 v105, 14, v105
	v_cndmask_b32_e32 v101, v101, v102, vcc
	v_mul_f32_e32 v102, 0x4b800000, v100
	v_rsq_f32_e32 v101, v101
	v_cndmask_b32_e64 v100, v100, v102, s[4:5]
	v_rsq_f32_e32 v100, v100
	v_cndmask_b32_e64 v102, v125, v122, s[0:1]
	v_mul_f32_e32 v103, 0x45800000, v101
	v_cndmask_b32_e32 v101, v101, v103, vcc
	v_mul_f32_e32 v103, 0x45800000, v100
	v_lshrrev_b32_e32 v122, 3, v1
	v_cndmask_b32_e64 v100, v100, v103, s[4:5]
	v_lshlrev_b32_e32 v103, 2, v118
	v_bitop3_b32 v124, v118, v122, 3 bitop3:0x6c
	s_waitcnt vmcnt(0)
	v_mul_f32_e32 v94, v94, v148
	v_add_lshl_u32 v123, v103, s46, 8
	v_lshl_add_u32 v124, v124, 4, s51
	v_and_b32_e32 v104, 3, v118
	v_cvt_pk_bf16_f32 v94, v94, v115
	v_add3_u32 v124, v124, v123, v105
	ds_write_b16 v124, v94
	v_mul_f32_e32 v94, v95, v102
	v_bitop3_b32 v95, v104, v122, 4 bitop3:0x36
	v_mul_f32_e32 v94, v148, v94
	v_lshl_add_u32 v95, v95, 4, s51
	v_cvt_pk_bf16_f32 v94, v94, v115
	v_add3_u32 v95, v95, v123, v105
	ds_write_b16 v95, v94 offset:256
	v_mul_f32_e32 v94, v96, v101
	v_bitop3_b32 v95, v104, v122, 8 bitop3:0x36
	v_mul_f32_e32 v94, v148, v94
	v_lshl_add_u32 v95, v95, 4, s51
	v_cvt_pk_bf16_f32 v94, v94, v115
	v_add3_u32 v95, v95, v123, v105
	ds_write_b16 v95, v94 offset:512
	v_mul_f32_e32 v94, v97, v100
	v_mul_f32_e32 v94, v148, v94
	v_cvt_pk_bf16_f32 v94, v94, v115
	v_mov_b32_e32 v95, v206
	v_bitop3_b32 v96, v104, v122, 12 bitop3:0x36
	v_lshl_add_u32 v96, v96, 4, s51
	v_add3_u32 v96, v96, v123, v105
	ds_write_b16 v96, v94 offset:768
	v_add_u32_e32 v94, 16, v1
	v_lshrrev_b32_e32 v94, 3, v94
	v_bitop3_b32 v96, v94, v118, 3 bitop3:0x78
	v_lshl_add_u32 v96, v96, 4, s51
	v_add3_u32 v96, v96, v123, v105
	v_mul_f32_e32 v86, v86, v119
	v_mul_f32_e32 v82, v82, v119
	v_mul_f32_e32 v78, v78, v119
	v_mul_f32_e32 v74, v74, v119
	v_mul_f32_e32 v62, v62, v119
	v_mul_f32_e32 v50, v50, v119
	s_waitcnt vmcnt(0)
	v_mul_f32_e32 v90, v90, v95
	v_cvt_pk_bf16_f32 v90, v90, v115
	ds_write_b16 v96, v90
	v_mul_f32_e32 v90, v91, v102
	v_bitop3_b32 v91, v104, v94, 4 bitop3:0x36
	v_mul_f32_e32 v90, v90, v95
	v_lshl_add_u32 v91, v91, 4, s51
	v_cvt_pk_bf16_f32 v90, v90, v115
	v_add3_u32 v91, v91, v123, v105
	ds_write_b16 v91, v90 offset:256
	v_mul_f32_e32 v90, v92, v101
	v_bitop3_b32 v91, v104, v94, 8 bitop3:0x36
	v_mul_f32_e32 v90, v90, v95
	v_lshl_add_u32 v91, v91, 4, s51
	v_cvt_pk_bf16_f32 v90, v90, v115
	v_add3_u32 v91, v91, v123, v105
	ds_write_b16 v91, v90 offset:512
	v_mul_f32_e32 v90, v93, v100
	v_mul_f32_e32 v90, v90, v95
	v_cvt_pk_bf16_f32 v90, v90, v115
	v_mov_b32_e32 v91, v207
	v_bitop3_b32 v92, v104, v94, 12 bitop3:0x36
	v_lshl_add_u32 v92, v92, 4, s51
	v_add3_u32 v92, v92, v123, v105
	ds_write_b16 v92, v90 offset:768
	v_add_u32_e32 v90, 32, v1
	v_lshrrev_b32_e32 v90, 3, v90
	v_bitop3_b32 v92, v90, v118, 3 bitop3:0x78
	v_lshl_add_u32 v92, v92, 4, s51
	v_add3_u32 v92, v92, v123, v105
	s_waitcnt vmcnt(0)
; __device__ __forceinline__ unsigned cvt_pk_bf16(float lo, float hi) { unsigned r; asm volatile("v_cvt_pk_bf16_f32 %0, %1, %2" : "=v"(r) : "v"(lo), "v"(hi)); return r; }
; #define LAS __attribute__((address_space(3)))
; #define LBAR() asm volatile("s_waitcnt lgkmcnt(0)\n\ts_barrier" ::: "memory")
; __device__ __forceinline__ void ret_phase(const Params& P, LAS unsigned char* lds, int tid, int lane, int wave, int bid, int G) {
;     ...
; #pragma unroll
;         for (int t = 0; t < 8; ++t) { const int dv = 16 * t + l15; const float gn = P.rgain[h * 128 + dv];
; #pragma unroll
;             for (int i = 0; i < 4; ++i) { const int n = w16 + 4 * g + i; const unsigned wv = cvt_pk_bf16(o[t][i] * rs[i] * gn, 0.f);
;                 *(LAS unsigned short*)(Pt + off256(n, dv >> 3) + 2 * (dv & 7)) = (unsigned short)(wv & 0xffffu); } }
;         LBAR();
	v_mul_f32_e32 v86, v86, v91
	v_cvt_pk_bf16_f32 v86, v86, v115
	ds_write_b16 v92, v86
	v_mul_f32_e32 v86, v87, v102
	v_bitop3_b32 v87, v104, v90, 4 bitop3:0x36
	v_mul_f32_e32 v86, v86, v91
	v_lshl_add_u32 v87, v87, 4, s51
	v_cvt_pk_bf16_f32 v86, v86, v115
	v_add3_u32 v87, v87, v123, v105
	ds_write_b16 v87, v86 offset:256
	v_mul_f32_e32 v86, v88, v101
	v_bitop3_b32 v87, v104, v90, 8 bitop3:0x36
	v_mul_f32_e32 v86, v86, v91
	v_lshl_add_u32 v87, v87, 4, s51
	v_cvt_pk_bf16_f32 v86, v86, v115
	v_add3_u32 v87, v87, v123, v105
	ds_write_b16 v87, v86 offset:512
	v_mul_f32_e32 v86, v89, v100
	v_mul_f32_e32 v86, v86, v91
	v_cvt_pk_bf16_f32 v86, v86, v115
	v_mov_b32_e32 v87, v208
	v_bitop3_b32 v88, v104, v90, 12 bitop3:0x36
	v_lshl_add_u32 v88, v88, 4, s51
	v_add3_u32 v88, v88, v123, v105
	ds_write_b16 v88, v86 offset:768
	v_add_u32_e32 v86, 48, v1
	v_lshrrev_b32_e32 v86, 3, v86
	v_bitop3_b32 v88, v86, v118, 3 bitop3:0x78
	v_lshl_add_u32 v88, v88, 4, s51
	v_add3_u32 v88, v88, v123, v105
	s_waitcnt vmcnt(0)
	v_mul_f32_e32 v82, v82, v87
	v_cvt_pk_bf16_f32 v82, v82, v115
	ds_write_b16 v88, v82
	v_mul_f32_e32 v82, v83, v102
	v_bitop3_b32 v83, v104, v86, 4 bitop3:0x36
	v_mul_f32_e32 v82, v82, v87
	v_lshl_add_u32 v83, v83, 4, s51
	v_cvt_pk_bf16_f32 v82, v82, v115
	v_add3_u32 v83, v83, v123, v105
	ds_write_b16 v83, v82 offset:256
	v_mul_f32_e32 v82, v84, v101
	v_bitop3_b32 v83, v104, v86, 8 bitop3:0x36
	v_mul_f32_e32 v82, v82, v87
	v_lshl_add_u32 v83, v83, 4, s51
	v_cvt_pk_bf16_f32 v82, v82, v115
	v_add3_u32 v83, v83, v123, v105
	ds_write_b16 v83, v82 offset:512
	v_mul_f32_e32 v82, v85, v100
	v_mul_f32_e32 v82, v82, v87
	v_cvt_pk_bf16_f32 v82, v82, v115
	v_mov_b32_e32 v83, v209
	v_bitop3_b32 v84, v104, v86, 12 bitop3:0x36
	v_lshl_add_u32 v84, v84, 4, s51
	v_add3_u32 v84, v84, v123, v105
	ds_write_b16 v84, v82 offset:768
	v_add_u32_e32 v82, 64, v1
	v_lshrrev_b32_e32 v82, 3, v82
	v_bitop3_b32 v84, v82, v118, 3 bitop3:0x78
	v_lshl_add_u32 v84, v84, 4, s51
	v_add3_u32 v84, v84, v123, v105
	s_waitcnt vmcnt(0)
	v_mul_f32_e32 v78, v78, v83
	v_cvt_pk_bf16_f32 v78, v78, v115
	ds_write_b16 v84, v78
	v_mul_f32_e32 v78, v79, v102
	v_bitop3_b32 v79, v104, v82, 4 bitop3:0x36
	v_mul_f32_e32 v78, v78, v83
	v_lshl_add_u32 v79, v79, 4, s51
	v_cvt_pk_bf16_f32 v78, v78, v115
	v_add3_u32 v79, v79, v123, v105
	ds_write_b16 v79, v78 offset:256
	v_mul_f32_e32 v78, v80, v101
	v_bitop3_b32 v79, v104, v82, 8 bitop3:0x36
	v_mul_f32_e32 v78, v78, v83
	v_lshl_add_u32 v79, v79, 4, s51
	v_cvt_pk_bf16_f32 v78, v78, v115
	v_add3_u32 v79, v79, v123, v105
	ds_write_b16 v79, v78 offset:512
	v_mul_f32_e32 v78, v81, v100
	v_mul_f32_e32 v78, v78, v83
	v_cvt_pk_bf16_f32 v78, v78, v115
	v_mov_b32_e32 v79, v210
	v_bitop3_b32 v80, v104, v82, 12 bitop3:0x36
	v_lshl_add_u32 v80, v80, 4, s51
	v_add3_u32 v80, v80, v123, v105
	ds_write_b16 v80, v78 offset:768
	v_add_u32_e32 v78, 0x50, v1
	v_lshrrev_b32_e32 v78, 3, v78
	v_bitop3_b32 v80, v78, v118, 3 bitop3:0x78
	v_lshl_add_u32 v80, v80, 4, s51
	v_add3_u32 v80, v80, v123, v105
	s_waitcnt vmcnt(0)
	v_mul_f32_e32 v74, v74, v79
	v_cvt_pk_bf16_f32 v74, v74, v115
	ds_write_b16 v80, v74
	v_mul_f32_e32 v74, v75, v102
	v_bitop3_b32 v75, v104, v78, 4 bitop3:0x36
	v_mul_f32_e32 v74, v74, v79
	v_lshl_add_u32 v75, v75, 4, s51
	v_cvt_pk_bf16_f32 v74, v74, v115
	v_add3_u32 v75, v75, v123, v105
	ds_write_b16 v75, v74 offset:256
	v_mul_f32_e32 v74, v76, v101
	v_bitop3_b32 v75, v104, v78, 8 bitop3:0x36
	v_mul_f32_e32 v74, v74, v79
	v_lshl_add_u32 v75, v75, 4, s51
	v_cvt_pk_bf16_f32 v74, v74, v115
	v_add3_u32 v75, v75, v123, v105
	ds_write_b16 v75, v74 offset:512
	v_mul_f32_e32 v74, v77, v100
	v_mul_f32_e32 v74, v74, v79
	v_cvt_pk_bf16_f32 v74, v74, v115
	v_mov_b32_e32 v75, v211
	v_bitop3_b32 v76, v104, v78, 12 bitop3:0x36
	v_lshl_add_u32 v76, v76, 4, s51
	v_add3_u32 v76, v76, v123, v105
	ds_write_b16 v76, v74 offset:768
	v_add_u32_e32 v74, 0x60, v1
	v_lshrrev_b32_e32 v74, 3, v74
	v_bitop3_b32 v76, v74, v118, 3 bitop3:0x78
	v_lshl_add_u32 v76, v76, 4, s51
	v_add3_u32 v76, v76, v123, v105
	v_and_b32_e32 v78, 12, v103
	s_waitcnt vmcnt(0)
	v_mul_f32_e32 v62, v62, v75
	v_cvt_pk_bf16_f32 v62, v62, v115
	ds_write_b16 v76, v62
	v_mul_f32_e32 v62, v63, v102
	v_bitop3_b32 v63, v104, v74, 4 bitop3:0x36
	v_mul_f32_e32 v62, v62, v75
	v_lshl_add_u32 v63, v63, 4, s51
	v_cvt_pk_bf16_f32 v62, v62, v115
	v_add3_u32 v63, v63, v123, v105
	ds_write_b16 v63, v62 offset:256
	v_mul_f32_e32 v62, v64, v101
	v_bitop3_b32 v63, v104, v74, 8 bitop3:0x36
	v_mul_f32_e32 v62, v62, v75
	v_lshl_add_u32 v63, v63, 4, s51
	v_cvt_pk_bf16_f32 v62, v62, v115
	v_add3_u32 v63, v63, v123, v105
	ds_write_b16 v63, v62 offset:512
	v_mul_f32_e32 v62, v65, v100
	v_mul_f32_e32 v62, v62, v75
	v_cvt_pk_bf16_f32 v62, v62, v115
	v_mov_b32_e32 v63, v212
	v_bitop3_b32 v64, v104, v74, 12 bitop3:0x36
	v_lshl_add_u32 v64, v64, 4, s51
	v_add3_u32 v64, v64, v123, v105
	ds_write_b16 v64, v62 offset:768
	v_add_u32_e32 v62, 0x70, v1
	v_lshrrev_b32_e32 v62, 3, v62
	v_bitop3_b32 v64, v62, v118, 3 bitop3:0x78
	v_lshl_add_u32 v64, v64, 4, s51
	v_add3_u32 v64, v64, v123, v105
	v_add_u32_e32 v74, s46, v118
	v_ashrrev_i32_e32 v75, 31, v74
	v_add_u32_e32 v76, 4, v74
	v_ashrrev_i32_e32 v77, 31, v76
	s_waitcnt vmcnt(0)
	v_mul_f32_e32 v50, v50, v63
	v_cvt_pk_bf16_f32 v50, v50, v115
	ds_write_b16 v64, v50
	v_mul_f32_e32 v50, v51, v102
	v_bitop3_b32 v51, v104, v62, 4 bitop3:0x36
	v_lshl_add_u32 v51, v51, 4, s51
	v_mul_f32_e32 v50, v50, v63
	v_add3_u32 v51, v51, v123, v105
	v_cvt_pk_bf16_f32 v50, v50, v115
	ds_write_b16 v51, v50 offset:256
	v_bitop3_b32 v51, v104, v62, 8 bitop3:0x36
	v_mul_f32_e32 v50, v52, v101
	v_lshl_add_u32 v51, v51, 4, s51
	v_mul_f32_e32 v50, v50, v63
	v_add3_u32 v51, v51, v123, v105
	v_cvt_pk_bf16_f32 v50, v50, v115
	ds_write_b16 v51, v50 offset:512
	v_bitop3_b32 v51, v104, v62, 12 bitop3:0x36
	v_mul_f32_e32 v50, v53, v100
	v_lshl_add_u32 v51, v51, 4, s51
	v_mul_f32_e32 v50, v50, v63
	v_add3_u32 v51, v51, v123, v105
	v_cvt_pk_bf16_f32 v50, v50, v115
	ds_write_b16 v51, v50 offset:768
	v_bfe_u32 v51, v118, 2, 2
	v_bitop3_b32 v51, v51, v1, v78 bitop3:0x36
	v_lshlrev_b32_e32 v50, 8, v74
	v_lshlrev_b32_e32 v51, 4, v51
	s_waitcnt lgkmcnt(0)
	s_barrier
; __device__ __forceinline__ unsigned cvt_pk_bf16(float lo, float hi) { unsigned r; asm volatile("v_cvt_pk_bf16_f32 %0, %1, %2" : "=v"(r) : "v"(lo), "v"(hi)); return r; }
; #define LAS __attribute__((address_space(3)))
; __device__ __forceinline__ float bf_lo(unsigned u) { return __uint_as_float(u << 16); }
; __device__ __forceinline__ float bf_hi(unsigned u) { return __uint_as_float(u & 0xffff0000u); }
; #define LBAR() asm volatile("s_waitcnt lgkmcnt(0)\n\ts_barrier" ::: "memory")
; __device__ __forceinline__ void ret_phase(const Params& P, LAS unsigned char* lds, int tid, int lane, int wave, int bid, int G) {
;     ...
; #pragma unroll
;         for (int it = 0; it < 4; ++it) { const int row = w16 + 4 * it + g, ch = l15;
;             const u32x4 ov = *(const LAS u32x4*)(Pt + off256(row, ch));
;             const u32x4 gv = grv[it];
;             u32x4 w; w.x = cvt_pk_bf16(bf_lo(ov.x) * bf_lo(gv.x), bf_hi(ov.x) * bf_hi(gv.x)); w.y = cvt_pk_bf16(bf_lo(ov.y) * bf_lo(gv.y), bf_hi(ov.y) * bf_hi(gv.y));
;             w.z = cvt_pk_bf16(bf_lo(ov.z) * bf_lo(gv.z), bf_hi(ov.z) * bf_hi(gv.z)); w.w = cvt_pk_bf16(bf_lo(ov.w) * bf_lo(gv.w), bf_hi(ov.w) * bf_hi(gv.w));
;             *(u32x4*)(MIX + (tokc + row) * DM + 512 + h * 128 + 8 * ch) = w; }
;         LBAR();
	v_add3_u32 v50, s51, v51, v50
	ds_read_b128 v[50:53], v50
	v_lshlrev_b32_e32 v64, 16, v70
	v_lshlrev_b32_e32 v62, 3, v1
	v_ashrrev_i32_e32 v63, 31, v62
	s_waitcnt lgkmcnt(0)
	v_lshlrev_b32_e32 v65, 16, v50
	v_mul_f32_e32 v64, v65, v64
	v_and_b32_e32 v50, 0xffff0000, v50
	v_and_b32_e32 v65, 0xffff0000, v70
	v_mul_f32_e32 v50, v50, v65
	v_cvt_pk_bf16_f32 v50, v64, v50
	v_lshlrev_b32_e32 v64, 16, v71
	v_lshlrev_b32_e32 v65, 16, v51
	v_mul_f32_e32 v64, v65, v64
	v_and_b32_e32 v51, 0xffff0000, v51
	v_and_b32_e32 v65, 0xffff0000, v71
	v_mul_f32_e32 v51, v51, v65
	v_cvt_pk_bf16_f32 v51, v64, v51
	v_lshlrev_b32_e32 v64, 16, v72
	v_lshlrev_b32_e32 v65, 16, v52
	v_mul_f32_e32 v64, v65, v64
	v_and_b32_e32 v52, 0xffff0000, v52
	v_and_b32_e32 v65, 0xffff0000, v72
	v_mul_f32_e32 v52, v52, v65
	v_cvt_pk_bf16_f32 v52, v64, v52
	v_lshlrev_b32_e32 v64, 16, v73
	v_lshlrev_b32_e32 v65, 16, v53
	v_mul_f32_e32 v64, v65, v64
	v_and_b32_e32 v53, 0xffff0000, v53
	v_and_b32_e32 v65, 0xffff0000, v73
	v_mul_f32_e32 v53, v53, v65
	v_cvt_pk_bf16_f32 v53, v64, v53
	v_lshl_add_u64 v[64:65], s[40:41], 0, v[74:75]
	v_lshlrev_b64 v[70:71], 1, v[62:63]
	v_bfe_u32 v63, v76, 2, 2
	v_lshlrev_b64 v[64:65], 11, v[64:65]
	v_bitop3_b32 v63, v63, v1, v78 bitop3:0x36
	v_lshl_add_u64 v[64:65], s[22:23], 0, v[64:65]
	v_lshlrev_b32_e32 v62, 8, v76
	v_lshlrev_b32_e32 v63, 4, v63
	v_lshl_add_u64 v[64:65], v[64:65], 0, s[18:19]
	v_add3_u32 v62, s51, v63, v62
	v_lshl_add_u64 v[72:73], v[64:65], 0, v[70:71]
	ds_read_b128 v[62:65], v62
	v_add_co_u32_e32 v72, vcc, s55, v72
	s_nop 1
	v_addc_co_u32_e32 v73, vcc, 0, v73, vcc
	global_store_dwordx4 v[72:73], v[50:53], off offset:1024
	s_nop 1
	v_lshlrev_b32_e32 v50, 16, v66
	s_waitcnt lgkmcnt(0)
	v_lshlrev_b32_e32 v51, 16, v62
	v_mul_f32_e32 v50, v51, v50
	v_and_b32_e32 v51, 0xffff0000, v62
	v_and_b32_e32 v52, 0xffff0000, v66
	v_mul_f32_e32 v51, v51, v52
	v_cvt_pk_bf16_f32 v50, v50, v51
	v_lshlrev_b32_e32 v51, 16, v67
	v_lshlrev_b32_e32 v52, 16, v63
	v_mul_f32_e32 v51, v52, v51
	v_and_b32_e32 v52, 0xffff0000, v63
	v_and_b32_e32 v53, 0xffff0000, v67
	v_mul_f32_e32 v52, v52, v53
	v_cvt_pk_bf16_f32 v51, v51, v52
	v_lshlrev_b32_e32 v52, 16, v68
	v_lshlrev_b32_e32 v53, 16, v64
	v_mul_f32_e32 v52, v53, v52
	v_and_b32_e32 v53, 0xffff0000, v64
	v_and_b32_e32 v62, 0xffff0000, v68
	v_mul_f32_e32 v53, v53, v62
	v_cvt_pk_bf16_f32 v52, v52, v53
	v_lshlrev_b32_e32 v53, 16, v69
	v_lshlrev_b32_e32 v62, 16, v65
	v_mul_f32_e32 v53, v62, v53
	v_and_b32_e32 v62, 0xffff0000, v65
	v_and_b32_e32 v63, 0xffff0000, v69
	v_mul_f32_e32 v62, v62, v63
	v_cvt_pk_bf16_f32 v53, v53, v62
	v_lshl_add_u64 v[62:63], s[40:41], 0, v[76:77]
	v_lshlrev_b64 v[62:63], 11, v[62:63]
	v_lshl_add_u64 v[62:63], s[22:23], 0, v[62:63]
	v_lshl_add_u64 v[62:63], v[62:63], 0, s[18:19]
	v_add_u32_e32 v68, 8, v74
	v_lshl_add_u64 v[66:67], v[62:63], 0, v[70:71]
	v_bfe_u32 v63, v68, 2, 2
	v_bitop3_b32 v63, v63, v1, v78 bitop3:0x36
	v_lshlrev_b32_e32 v62, 8, v68
	v_lshlrev_b32_e32 v63, 4, v63
	v_add3_u32 v62, s51, v63, v62
	ds_read_b128 v[62:65], v62
	v_add_co_u32_e32 v66, vcc, s55, v66
	v_ashrrev_i32_e32 v69, 31, v68
	s_nop 0
	v_addc_co_u32_e32 v67, vcc, 0, v67, vcc
	global_store_dwordx4 v[66:67], v[50:53], off offset:1024
	s_nop 1
	v_lshlrev_b32_e32 v50, 16, v58
	s_waitcnt lgkmcnt(0)
	v_lshlrev_b32_e32 v51, 16, v62
	v_mul_f32_e32 v50, v51, v50
	v_and_b32_e32 v51, 0xffff0000, v62
	v_and_b32_e32 v52, 0xffff0000, v58
	v_mul_f32_e32 v51, v51, v52
	v_cvt_pk_bf16_f32 v50, v50, v51
	v_lshlrev_b32_e32 v51, 16, v59
	v_lshlrev_b32_e32 v52, 16, v63
	v_mul_f32_e32 v51, v52, v51
	v_and_b32_e32 v52, 0xffff0000, v63
	v_and_b32_e32 v53, 0xffff0000, v59
	v_mul_f32_e32 v52, v52, v53
	v_cvt_pk_bf16_f32 v51, v51, v52
	v_lshlrev_b32_e32 v52, 16, v60
	v_lshlrev_b32_e32 v53, 16, v64
	v_mul_f32_e32 v52, v53, v52
	v_and_b32_e32 v53, 0xffff0000, v64
	v_and_b32_e32 v58, 0xffff0000, v60
	v_mul_f32_e32 v53, v53, v58
	v_cvt_pk_bf16_f32 v52, v52, v53
	v_lshlrev_b32_e32 v53, 16, v61
	v_lshlrev_b32_e32 v58, 16, v65
	v_mul_f32_e32 v53, v58, v53
	v_and_b32_e32 v58, 0xffff0000, v65
	v_and_b32_e32 v59, 0xffff0000, v61
	v_mul_f32_e32 v58, v58, v59
	v_cvt_pk_bf16_f32 v53, v53, v58
	v_lshl_add_u64 v[58:59], s[40:41], 0, v[68:69]
	v_lshlrev_b64 v[58:59], 11, v[58:59]
	v_lshl_add_u64 v[58:59], s[22:23], 0, v[58:59]
	v_lshl_add_u64 v[58:59], v[58:59], 0, s[18:19]
	v_add_u32_e32 v64, 12, v74
	v_lshl_add_u64 v[62:63], v[58:59], 0, v[70:71]
	v_bfe_u32 v59, v64, 2, 2
	v_bitop3_b32 v59, v59, v1, v78 bitop3:0x36
	v_lshlrev_b32_e32 v58, 8, v64
	v_lshlrev_b32_e32 v59, 4, v59
	v_add3_u32 v58, s51, v59, v58
	ds_read_b128 v[58:61], v58
	v_add_co_u32_e32 v62, vcc, s55, v62
	v_ashrrev_i32_e32 v65, 31, v64
	s_nop 0
	v_addc_co_u32_e32 v63, vcc, 0, v63, vcc
	global_store_dwordx4 v[62:63], v[50:53], off offset:1024
	s_nop 1
	v_lshlrev_b32_e32 v50, 16, v54
	s_waitcnt lgkmcnt(0)
	v_lshlrev_b32_e32 v51, 16, v58
	v_mul_f32_e32 v50, v51, v50
	v_and_b32_e32 v51, 0xffff0000, v58
	v_and_b32_e32 v52, 0xffff0000, v54
	v_mul_f32_e32 v51, v51, v52
	v_cvt_pk_bf16_f32 v50, v50, v51
	v_lshlrev_b32_e32 v51, 16, v55
	v_lshlrev_b32_e32 v52, 16, v59
	v_mul_f32_e32 v51, v52, v51
	v_and_b32_e32 v52, 0xffff0000, v59
	v_and_b32_e32 v53, 0xffff0000, v55
	v_mul_f32_e32 v52, v52, v53
	v_cvt_pk_bf16_f32 v51, v51, v52
	v_lshlrev_b32_e32 v52, 16, v56
	v_lshlrev_b32_e32 v53, 16, v60
	v_mul_f32_e32 v52, v53, v52
	v_and_b32_e32 v53, 0xffff0000, v60
	v_and_b32_e32 v54, 0xffff0000, v56
	v_mul_f32_e32 v53, v53, v54
	v_cvt_pk_bf16_f32 v52, v52, v53
	v_lshlrev_b32_e32 v53, 16, v57
	v_lshlrev_b32_e32 v54, 16, v61
	v_mul_f32_e32 v53, v54, v53
	v_and_b32_e32 v54, 0xffff0000, v61
	v_and_b32_e32 v55, 0xffff0000, v57
	v_mul_f32_e32 v54, v54, v55
	v_cvt_pk_bf16_f32 v53, v53, v54
	v_lshl_add_u64 v[54:55], s[40:41], 0, v[64:65]
	v_lshlrev_b64 v[54:55], 11, v[54:55]
	v_lshl_add_u64 v[54:55], s[22:23], 0, v[54:55]
	v_lshl_add_u64 v[54:55], v[54:55], 0, s[18:19]
	v_lshl_add_u64 v[54:55], v[54:55], 0, v[70:71]
	v_add_co_u32_e32 v54, vcc, 0x2000000, v54
	s_nop 1
	v_addc_co_u32_e32 v55, vcc, 0, v55, vcc
	global_store_dwordx4 v[54:55], v[50:53], off offset:1024
	s_waitcnt lgkmcnt(0)
	s_barrier
	s_andn2_b64 vcc, exec, s[42:43]
	s_cbranch_vccz .LBB0_393
